# dead padding before the FFN-down phase grown by 64 B (code placement of the FFN-down K-loop)
# speedup vs baseline: 1.0233x; 1.0044x over previous
.Lffn_nz:
	s_waitcnt vmcnt(0)
	ds_bpermute_b32 v200, v252, v158
	ds_bpermute_b32 v201, v252, v159
	ds_bpermute_b32 v202, v252, v154
	ds_bpermute_b32 v203, v252, v155
	s_waitcnt lgkmcnt(0)
	ds_bpermute_b32 v204, v252, v62
	ds_bpermute_b32 v205, v252, v63
	ds_bpermute_b32 v206, v252, v58
	ds_bpermute_b32 v207, v252, v59
	v_pk_fma_f32 v[230:231], v[156:157], v[112:113], v[116:117] op_sel_hi:[1,0,0]
	v_pk_fma_f32 v[232:233], v[158:159], v[112:113], v[116:117] op_sel_hi:[1,0,0]
	v_fmac_f32_e32 v230, v201, v113
	v_fmac_f32_e32 v231, v156, v113
	v_fmac_f32_e32 v232, v157, v113
	v_fmac_f32_e32 v233, v158, v113
	v_pk_fma_f32 v[230:231], v[200:201], v[114:115], v[230:231] op_sel_hi:[1,0,1]
	v_pk_fma_f32 v[232:233], v[156:157], v[114:115], v[232:233] op_sel_hi:[1,0,1]
	v_pk_fma_f32 v[234:235], v[152:153], v[118:119], v[122:123] op_sel_hi:[1,0,0]
	v_pk_fma_f32 v[236:237], v[154:155], v[118:119], v[122:123] op_sel_hi:[1,0,0]
	v_fmac_f32_e32 v234, v203, v119
	v_fmac_f32_e32 v235, v152, v119
	v_fmac_f32_e32 v236, v153, v119
	v_fmac_f32_e32 v237, v154, v119
	v_pk_fma_f32 v[234:235], v[202:203], v[120:121], v[234:235] op_sel_hi:[1,0,1]
	v_pk_fma_f32 v[236:237], v[152:153], v[120:121], v[236:237] op_sel_hi:[1,0,1]
	v_pk_mul_f32 v[238:239], v[230:231], v[230:231]
	v_pk_mul_f32 v[240:241], v[232:233], v[232:233]
	v_pk_fma_f32 v[238:239], v[238:239], v[248:249], v[246:247]
	v_pk_fma_f32 v[240:241], v[240:241], v[248:249], v[246:247]
	v_pk_mul_f32 v[238:239], v[230:231], v[238:239]
	v_pk_mul_f32 v[240:241], v[232:233], v[240:241]
	v_exp_f32_e32 v238, v238
	v_exp_f32_e32 v239, v239
	v_exp_f32_e32 v240, v240
	v_exp_f32_e32 v241, v241
	v_pk_add_f32 v[238:239], v[238:239], 1.0 op_sel_hi:[1,0]
	v_pk_add_f32 v[240:241], v[240:241], 1.0 op_sel_hi:[1,0]
	v_rcp_f32_e32 v238, v238
	v_rcp_f32_e32 v239, v239
	v_rcp_f32_e32 v240, v240
	v_rcp_f32_e32 v241, v241
	v_pk_mul_f32 v[230:231], v[230:231], v[234:235]
	v_pk_mul_f32 v[232:233], v[232:233], v[236:237]
	v_pk_mul_f32 v[238:239], v[230:231], v[238:239]
	v_pk_mul_f32 v[240:241], v[232:233], v[240:241]
	v_cvt_pk_bf16_f32 v212, v238, v239
	v_cvt_pk_bf16_f32 v213, v240, v241
	s_mov_b64 vcc, s[30:31]
	s_nop 0
	v_mov_b32_dpp v214, v212 quad_perm:[1,0,3,2] row_mask:0xf bank_mask:0xf
	v_mov_b32_dpp v215, v213 quad_perm:[1,0,3,2] row_mask:0xf bank_mask:0xf
	v_perm_b32 v216, v214, v212, v253
	v_perm_b32 v217, v215, v213, v253
	s_nop 1
	v_mov_b32_dpp v218, v216 quad_perm:[2,3,0,1] row_mask:0xf bank_mask:0xf
	v_mov_b32_dpp v219, v217 quad_perm:[2,3,0,1] row_mask:0xf bank_mask:0xf
	v_cndmask_b32_e32 v176, v216, v219, vcc
	v_cndmask_b32_e32 v177, v218, v217, vcc
	s_waitcnt lgkmcnt(0)
	s_mov_b64 vcc, s[28:29]
	v_cndmask_b32_e32 v208, v150, v158, vcc
	v_cndmask_b32_e32 v209, v151, v159, vcc
	v_cndmask_b32_e32 v210, v146, v154, vcc
	v_cndmask_b32_e32 v211, v147, v155, vcc
	ds_bpermute_b32 v200, v252, v208
	ds_bpermute_b32 v201, v252, v209
	ds_bpermute_b32 v202, v252, v210
	ds_bpermute_b32 v203, v252, v211
	v_pk_fma_f32 v[230:231], v[60:61], v[124:125], v[128:129] op_sel_hi:[1,0,0]
	v_pk_fma_f32 v[232:233], v[62:63], v[124:125], v[128:129] op_sel_hi:[1,0,0]
	v_fmac_f32_e32 v230, v205, v125
	v_fmac_f32_e32 v231, v60, v125
	v_fmac_f32_e32 v232, v61, v125
	v_fmac_f32_e32 v233, v62, v125
	v_pk_fma_f32 v[230:231], v[204:205], v[126:127], v[230:231] op_sel_hi:[1,0,1]
	v_pk_fma_f32 v[232:233], v[60:61], v[126:127], v[232:233] op_sel_hi:[1,0,1]
	v_pk_fma_f32 v[234:235], v[56:57], v[130:131], v[134:135] op_sel_hi:[1,0,0]
	v_pk_fma_f32 v[236:237], v[58:59], v[130:131], v[134:135] op_sel_hi:[1,0,0]
	v_fmac_f32_e32 v234, v207, v131
	v_fmac_f32_e32 v235, v56, v131
	v_fmac_f32_e32 v236, v57, v131
	v_fmac_f32_e32 v237, v58, v131
	v_pk_fma_f32 v[234:235], v[206:207], v[132:133], v[234:235] op_sel_hi:[1,0,1]
	v_pk_fma_f32 v[236:237], v[56:57], v[132:133], v[236:237] op_sel_hi:[1,0,1]
	v_pk_mul_f32 v[238:239], v[230:231], v[230:231]
	v_pk_mul_f32 v[240:241], v[232:233], v[232:233]
	v_pk_fma_f32 v[238:239], v[238:239], v[248:249], v[246:247]
	v_pk_fma_f32 v[240:241], v[240:241], v[248:249], v[246:247]
	v_pk_mul_f32 v[238:239], v[230:231], v[238:239]
	v_pk_mul_f32 v[240:241], v[232:233], v[240:241]
	v_exp_f32_e32 v238, v238
	v_exp_f32_e32 v239, v239
	v_exp_f32_e32 v240, v240
	v_exp_f32_e32 v241, v241
	v_pk_add_f32 v[238:239], v[238:239], 1.0 op_sel_hi:[1,0]
	v_pk_add_f32 v[240:241], v[240:241], 1.0 op_sel_hi:[1,0]
	v_rcp_f32_e32 v238, v238
	v_rcp_f32_e32 v239, v239
	v_rcp_f32_e32 v240, v240
	v_rcp_f32_e32 v241, v241
	v_pk_mul_f32 v[230:231], v[230:231], v[234:235]
	v_pk_mul_f32 v[232:233], v[232:233], v[236:237]
	v_pk_mul_f32 v[238:239], v[230:231], v[238:239]
	v_pk_mul_f32 v[240:241], v[232:233], v[240:241]
	v_cvt_pk_bf16_f32 v212, v238, v239
	v_cvt_pk_bf16_f32 v213, v240, v241
	s_mov_b64 vcc, s[30:31]
	s_nop 0
	v_mov_b32_dpp v214, v212 quad_perm:[1,0,3,2] row_mask:0xf bank_mask:0xf
	v_mov_b32_dpp v215, v213 quad_perm:[1,0,3,2] row_mask:0xf bank_mask:0xf
	v_perm_b32 v216, v214, v212, v253
	v_perm_b32 v217, v215, v213, v253
	s_nop 1
	v_mov_b32_dpp v218, v216 quad_perm:[2,3,0,1] row_mask:0xf bank_mask:0xf
	v_mov_b32_dpp v219, v217 quad_perm:[2,3,0,1] row_mask:0xf bank_mask:0xf
	v_cndmask_b32_e32 v178, v216, v219, vcc
	v_cndmask_b32_e32 v179, v218, v217, vcc
	s_movk_i32 s15, 0x1002
	v_cmp_gt_i32_e64 s[24:25], s15, v251
	s_sub_u32 s84, s58, 0x2c00
	s_subb_u32 s85, s59, 0
	s_and_b64 s[24:25], s[24:25], s[36:37]
	s_mov_b64 exec, s[24:25]
	global_store_dwordx4 v250, v[176:179], s[84:85] nt
	s_mov_b64 exec, -1
	s_nop 0
	s_waitcnt lgkmcnt(0)
	s_mov_b64 vcc, s[28:29]
	v_cndmask_b32_e32 v208, v54, v62, vcc
	v_cndmask_b32_e32 v209, v55, v63, vcc
	v_cndmask_b32_e32 v210, v50, v58, vcc
	v_cndmask_b32_e32 v211, v51, v59, vcc
	ds_bpermute_b32 v204, v252, v208
	ds_bpermute_b32 v205, v252, v209
	ds_bpermute_b32 v206, v252, v210
	ds_bpermute_b32 v207, v252, v211
	v_pk_fma_f32 v[230:231], v[148:149], v[112:113], v[116:117] op_sel_hi:[1,0,0]
	v_pk_fma_f32 v[232:233], v[150:151], v[112:113], v[116:117] op_sel_hi:[1,0,0]
	v_fmac_f32_e32 v230, v201, v113
	v_fmac_f32_e32 v231, v148, v113
	v_fmac_f32_e32 v232, v149, v113
	v_fmac_f32_e32 v233, v150, v113
	v_pk_fma_f32 v[230:231], v[200:201], v[114:115], v[230:231] op_sel_hi:[1,0,1]
	v_pk_fma_f32 v[232:233], v[148:149], v[114:115], v[232:233] op_sel_hi:[1,0,1]
	v_pk_fma_f32 v[234:235], v[144:145], v[118:119], v[122:123] op_sel_hi:[1,0,0]
	v_pk_fma_f32 v[236:237], v[146:147], v[118:119], v[122:123] op_sel_hi:[1,0,0]
	v_fmac_f32_e32 v234, v203, v119
	v_fmac_f32_e32 v235, v144, v119
	v_fmac_f32_e32 v236, v145, v119
	v_fmac_f32_e32 v237, v146, v119
	v_pk_fma_f32 v[234:235], v[202:203], v[120:121], v[234:235] op_sel_hi:[1,0,1]
	v_pk_fma_f32 v[236:237], v[144:145], v[120:121], v[236:237] op_sel_hi:[1,0,1]
	v_pk_mul_f32 v[238:239], v[230:231], v[230:231]
	v_pk_mul_f32 v[240:241], v[232:233], v[232:233]
	v_pk_fma_f32 v[238:239], v[238:239], v[248:249], v[246:247]
	v_pk_fma_f32 v[240:241], v[240:241], v[248:249], v[246:247]
	v_pk_mul_f32 v[238:239], v[230:231], v[238:239]
	v_pk_mul_f32 v[240:241], v[232:233], v[240:241]
	v_exp_f32_e32 v238, v238
	v_exp_f32_e32 v239, v239
	v_exp_f32_e32 v240, v240
	v_exp_f32_e32 v241, v241
	v_pk_add_f32 v[238:239], v[238:239], 1.0 op_sel_hi:[1,0]
	v_pk_add_f32 v[240:241], v[240:241], 1.0 op_sel_hi:[1,0]
	v_rcp_f32_e32 v238, v238
	v_rcp_f32_e32 v239, v239
	v_rcp_f32_e32 v240, v240
	v_rcp_f32_e32 v241, v241
	v_pk_mul_f32 v[230:231], v[230:231], v[234:235]
	v_pk_mul_f32 v[232:233], v[232:233], v[236:237]
	v_pk_mul_f32 v[238:239], v[230:231], v[238:239]
	v_pk_mul_f32 v[240:241], v[232:233], v[240:241]
	v_cvt_pk_bf16_f32 v212, v238, v239
	v_cvt_pk_bf16_f32 v213, v240, v241
	s_mov_b64 vcc, s[30:31]
	s_nop 0
	v_mov_b32_dpp v214, v212 quad_perm:[1,0,3,2] row_mask:0xf bank_mask:0xf
	v_mov_b32_dpp v215, v213 quad_perm:[1,0,3,2] row_mask:0xf bank_mask:0xf
	v_perm_b32 v216, v214, v212, v253
	v_perm_b32 v217, v215, v213, v253
	s_nop 1
	v_mov_b32_dpp v218, v216 quad_perm:[2,3,0,1] row_mask:0xf bank_mask:0xf
	v_mov_b32_dpp v219, v217 quad_perm:[2,3,0,1] row_mask:0xf bank_mask:0xf
	v_cndmask_b32_e32 v180, v216, v219, vcc
	v_cndmask_b32_e32 v181, v218, v217, vcc
	s_waitcnt lgkmcnt(0)
	s_mov_b64 vcc, s[28:29]
	v_cndmask_b32_e32 v208, v142, v150, vcc
	v_cndmask_b32_e32 v209, v143, v151, vcc
	v_cndmask_b32_e32 v210, v138, v146, vcc
	v_cndmask_b32_e32 v211, v139, v147, vcc
	ds_bpermute_b32 v200, v252, v208
	ds_bpermute_b32 v201, v252, v209
	ds_bpermute_b32 v202, v252, v210
	ds_bpermute_b32 v203, v252, v211
	v_pk_fma_f32 v[230:231], v[52:53], v[124:125], v[128:129] op_sel_hi:[1,0,0]
	v_pk_fma_f32 v[232:233], v[54:55], v[124:125], v[128:129] op_sel_hi:[1,0,0]
	v_fmac_f32_e32 v230, v205, v125
	v_fmac_f32_e32 v231, v52, v125
	v_fmac_f32_e32 v232, v53, v125
	v_fmac_f32_e32 v233, v54, v125
	v_pk_fma_f32 v[230:231], v[204:205], v[126:127], v[230:231] op_sel_hi:[1,0,1]
	v_pk_fma_f32 v[232:233], v[52:53], v[126:127], v[232:233] op_sel_hi:[1,0,1]
	v_pk_fma_f32 v[234:235], v[48:49], v[130:131], v[134:135] op_sel_hi:[1,0,0]
	v_pk_fma_f32 v[236:237], v[50:51], v[130:131], v[134:135] op_sel_hi:[1,0,0]
	v_fmac_f32_e32 v234, v207, v131
	v_fmac_f32_e32 v235, v48, v131
	v_fmac_f32_e32 v236, v49, v131
	v_fmac_f32_e32 v237, v50, v131
	v_pk_fma_f32 v[234:235], v[206:207], v[132:133], v[234:235] op_sel_hi:[1,0,1]
	v_pk_fma_f32 v[236:237], v[48:49], v[132:133], v[236:237] op_sel_hi:[1,0,1]
	v_pk_mul_f32 v[238:239], v[230:231], v[230:231]
	v_pk_mul_f32 v[240:241], v[232:233], v[232:233]
	v_pk_fma_f32 v[238:239], v[238:239], v[248:249], v[246:247]
	v_pk_fma_f32 v[240:241], v[240:241], v[248:249], v[246:247]
	v_pk_mul_f32 v[238:239], v[230:231], v[238:239]
	v_pk_mul_f32 v[240:241], v[232:233], v[240:241]
	v_exp_f32_e32 v238, v238
	v_exp_f32_e32 v239, v239
	v_exp_f32_e32 v240, v240
	v_exp_f32_e32 v241, v241
	v_pk_add_f32 v[238:239], v[238:239], 1.0 op_sel_hi:[1,0]
	v_pk_add_f32 v[240:241], v[240:241], 1.0 op_sel_hi:[1,0]
	v_rcp_f32_e32 v238, v238
	v_rcp_f32_e32 v239, v239
	v_rcp_f32_e32 v240, v240
	v_rcp_f32_e32 v241, v241
	v_pk_mul_f32 v[230:231], v[230:231], v[234:235]
	v_pk_mul_f32 v[232:233], v[232:233], v[236:237]
	v_pk_mul_f32 v[238:239], v[230:231], v[238:239]
	v_pk_mul_f32 v[240:241], v[232:233], v[240:241]
	v_cvt_pk_bf16_f32 v212, v238, v239
	v_cvt_pk_bf16_f32 v213, v240, v241
	s_mov_b64 vcc, s[30:31]
	s_nop 0
	v_mov_b32_dpp v214, v212 quad_perm:[1,0,3,2] row_mask:0xf bank_mask:0xf
	v_mov_b32_dpp v215, v213 quad_perm:[1,0,3,2] row_mask:0xf bank_mask:0xf
	v_perm_b32 v216, v214, v212, v253
	v_perm_b32 v217, v215, v213, v253
	s_nop 1
	v_mov_b32_dpp v218, v216 quad_perm:[2,3,0,1] row_mask:0xf bank_mask:0xf
	v_mov_b32_dpp v219, v217 quad_perm:[2,3,0,1] row_mask:0xf bank_mask:0xf
	v_cndmask_b32_e32 v182, v216, v219, vcc
	v_cndmask_b32_e32 v183, v218, v217, vcc
	s_movk_i32 s15, 0xff2
	v_cmp_gt_i32_e64 s[24:25], s15, v251
	s_add_u32 s84, s58, 0x13400
	s_addc_u32 s85, s59, 0
	s_mov_b64 exec, s[24:25]
	global_store_dwordx4 v250, v[180:183], s[84:85] nt
	s_mov_b64 exec, -1
	s_nop 0
	s_waitcnt lgkmcnt(0)
	s_mov_b64 vcc, s[28:29]
	v_cndmask_b32_e32 v208, v46, v54, vcc
	v_cndmask_b32_e32 v209, v47, v55, vcc
	v_cndmask_b32_e32 v210, v42, v50, vcc
	v_cndmask_b32_e32 v211, v43, v51, vcc
	ds_bpermute_b32 v204, v252, v208
	ds_bpermute_b32 v205, v252, v209
	ds_bpermute_b32 v206, v252, v210
	ds_bpermute_b32 v207, v252, v211
	v_pk_fma_f32 v[230:231], v[140:141], v[112:113], v[116:117] op_sel_hi:[1,0,0]
	v_pk_fma_f32 v[232:233], v[142:143], v[112:113], v[116:117] op_sel_hi:[1,0,0]
	v_fmac_f32_e32 v230, v201, v113
	v_fmac_f32_e32 v231, v140, v113
	v_fmac_f32_e32 v232, v141, v113
	v_fmac_f32_e32 v233, v142, v113
	v_pk_fma_f32 v[230:231], v[200:201], v[114:115], v[230:231] op_sel_hi:[1,0,1]
	v_pk_fma_f32 v[232:233], v[140:141], v[114:115], v[232:233] op_sel_hi:[1,0,1]
	v_pk_fma_f32 v[234:235], v[136:137], v[118:119], v[122:123] op_sel_hi:[1,0,0]
	v_pk_fma_f32 v[236:237], v[138:139], v[118:119], v[122:123] op_sel_hi:[1,0,0]
	v_fmac_f32_e32 v234, v203, v119
	v_fmac_f32_e32 v235, v136, v119
	v_fmac_f32_e32 v236, v137, v119
	v_fmac_f32_e32 v237, v138, v119
	v_pk_fma_f32 v[234:235], v[202:203], v[120:121], v[234:235] op_sel_hi:[1,0,1]
	v_pk_fma_f32 v[236:237], v[136:137], v[120:121], v[236:237] op_sel_hi:[1,0,1]
	v_pk_mul_f32 v[238:239], v[230:231], v[230:231]
	v_pk_mul_f32 v[240:241], v[232:233], v[232:233]
	v_pk_fma_f32 v[238:239], v[238:239], v[248:249], v[246:247]
	v_pk_fma_f32 v[240:241], v[240:241], v[248:249], v[246:247]
	v_pk_mul_f32 v[238:239], v[230:231], v[238:239]
	v_pk_mul_f32 v[240:241], v[232:233], v[240:241]
	v_exp_f32_e32 v238, v238
	v_exp_f32_e32 v239, v239
	v_exp_f32_e32 v240, v240
	v_exp_f32_e32 v241, v241
	v_pk_add_f32 v[238:239], v[238:239], 1.0 op_sel_hi:[1,0]
	v_pk_add_f32 v[240:241], v[240:241], 1.0 op_sel_hi:[1,0]
	v_rcp_f32_e32 v238, v238
	v_rcp_f32_e32 v239, v239
	v_rcp_f32_e32 v240, v240
	v_rcp_f32_e32 v241, v241
	v_pk_mul_f32 v[230:231], v[230:231], v[234:235]
	v_pk_mul_f32 v[232:233], v[232:233], v[236:237]
	v_pk_mul_f32 v[238:239], v[230:231], v[238:239]
	v_pk_mul_f32 v[240:241], v[232:233], v[240:241]
	v_cvt_pk_bf16_f32 v212, v238, v239
	v_cvt_pk_bf16_f32 v213, v240, v241
	s_mov_b64 vcc, s[30:31]
	s_nop 0
	v_mov_b32_dpp v214, v212 quad_perm:[1,0,3,2] row_mask:0xf bank_mask:0xf
	v_mov_b32_dpp v215, v213 quad_perm:[1,0,3,2] row_mask:0xf bank_mask:0xf
	v_perm_b32 v216, v214, v212, v253
	v_perm_b32 v217, v215, v213, v253
	s_nop 1
	v_mov_b32_dpp v218, v216 quad_perm:[2,3,0,1] row_mask:0xf bank_mask:0xf
	v_mov_b32_dpp v219, v217 quad_perm:[2,3,0,1] row_mask:0xf bank_mask:0xf
	v_cndmask_b32_e32 v176, v216, v219, vcc
	v_cndmask_b32_e32 v177, v218, v217, vcc
	s_waitcnt lgkmcnt(0)
	s_mov_b64 vcc, s[28:29]
	v_cndmask_b32_e32 v208, v110, v142, vcc
	v_cndmask_b32_e32 v209, v111, v143, vcc
	v_cndmask_b32_e32 v210, v98, v138, vcc
	v_cndmask_b32_e32 v211, v99, v139, vcc
	ds_bpermute_b32 v200, v252, v208
	ds_bpermute_b32 v201, v252, v209
	ds_bpermute_b32 v202, v252, v210
	ds_bpermute_b32 v203, v252, v211
	v_pk_fma_f32 v[230:231], v[44:45], v[124:125], v[128:129] op_sel_hi:[1,0,0]
	v_pk_fma_f32 v[232:233], v[46:47], v[124:125], v[128:129] op_sel_hi:[1,0,0]
	v_fmac_f32_e32 v230, v205, v125
	v_fmac_f32_e32 v231, v44, v125
	v_fmac_f32_e32 v232, v45, v125
	v_fmac_f32_e32 v233, v46, v125
	v_pk_fma_f32 v[230:231], v[204:205], v[126:127], v[230:231] op_sel_hi:[1,0,1]
	v_pk_fma_f32 v[232:233], v[44:45], v[126:127], v[232:233] op_sel_hi:[1,0,1]
	v_pk_fma_f32 v[234:235], v[40:41], v[130:131], v[134:135] op_sel_hi:[1,0,0]
	v_pk_fma_f32 v[236:237], v[42:43], v[130:131], v[134:135] op_sel_hi:[1,0,0]
	v_fmac_f32_e32 v234, v207, v131
	v_fmac_f32_e32 v235, v40, v131
	v_fmac_f32_e32 v236, v41, v131
	v_fmac_f32_e32 v237, v42, v131
	v_pk_fma_f32 v[234:235], v[206:207], v[132:133], v[234:235] op_sel_hi:[1,0,1]
	v_pk_fma_f32 v[236:237], v[40:41], v[132:133], v[236:237] op_sel_hi:[1,0,1]
	v_pk_mul_f32 v[238:239], v[230:231], v[230:231]
	v_pk_mul_f32 v[240:241], v[232:233], v[232:233]
	v_pk_fma_f32 v[238:239], v[238:239], v[248:249], v[246:247]
	v_pk_fma_f32 v[240:241], v[240:241], v[248:249], v[246:247]
	v_pk_mul_f32 v[238:239], v[230:231], v[238:239]
	v_pk_mul_f32 v[240:241], v[232:233], v[240:241]
	v_exp_f32_e32 v238, v238
	v_exp_f32_e32 v239, v239
	v_exp_f32_e32 v240, v240
	v_exp_f32_e32 v241, v241
	v_pk_add_f32 v[238:239], v[238:239], 1.0 op_sel_hi:[1,0]
	v_pk_add_f32 v[240:241], v[240:241], 1.0 op_sel_hi:[1,0]
	v_rcp_f32_e32 v238, v238
	v_rcp_f32_e32 v239, v239
	v_rcp_f32_e32 v240, v240
	v_rcp_f32_e32 v241, v241
	v_pk_mul_f32 v[230:231], v[230:231], v[234:235]
	v_pk_mul_f32 v[232:233], v[232:233], v[236:237]
	v_pk_mul_f32 v[238:239], v[230:231], v[238:239]
	v_pk_mul_f32 v[240:241], v[232:233], v[240:241]
	v_cvt_pk_bf16_f32 v212, v238, v239
	v_cvt_pk_bf16_f32 v213, v240, v241
	s_mov_b64 vcc, s[30:31]
	s_nop 0
	v_mov_b32_dpp v214, v212 quad_perm:[1,0,3,2] row_mask:0xf bank_mask:0xf
	v_mov_b32_dpp v215, v213 quad_perm:[1,0,3,2] row_mask:0xf bank_mask:0xf
	v_perm_b32 v216, v214, v212, v253
	v_perm_b32 v217, v215, v213, v253
	s_nop 1
	v_mov_b32_dpp v218, v216 quad_perm:[2,3,0,1] row_mask:0xf bank_mask:0xf
	v_mov_b32_dpp v219, v217 quad_perm:[2,3,0,1] row_mask:0xf bank_mask:0xf
	v_cndmask_b32_e32 v178, v216, v219, vcc
	v_cndmask_b32_e32 v179, v218, v217, vcc
	s_movk_i32 s15, 0xfe2
	v_cmp_gt_i32_e64 s[24:25], s15, v251
	s_add_u32 s84, s58, 0x29400
	s_addc_u32 s85, s59, 0
	s_mov_b64 exec, s[24:25]
	global_store_dwordx4 v250, v[176:179], s[84:85] nt
	s_mov_b64 exec, -1
	s_nop 0
	s_waitcnt lgkmcnt(0)
	s_mov_b64 vcc, s[28:29]
	v_cndmask_b32_e32 v208, v38, v46, vcc
	v_cndmask_b32_e32 v209, v39, v47, vcc
	v_cndmask_b32_e32 v210, v34, v42, vcc
	v_cndmask_b32_e32 v211, v35, v43, vcc
	ds_bpermute_b32 v204, v252, v208
	ds_bpermute_b32 v205, v252, v209
	ds_bpermute_b32 v206, v252, v210
	ds_bpermute_b32 v207, v252, v211
	v_pk_fma_f32 v[230:231], v[108:109], v[112:113], v[116:117] op_sel_hi:[1,0,0]
	v_pk_fma_f32 v[232:233], v[110:111], v[112:113], v[116:117] op_sel_hi:[1,0,0]
	v_fmac_f32_e32 v230, v201, v113
	v_fmac_f32_e32 v231, v108, v113
	v_fmac_f32_e32 v232, v109, v113
	v_fmac_f32_e32 v233, v110, v113
	v_pk_fma_f32 v[230:231], v[200:201], v[114:115], v[230:231] op_sel_hi:[1,0,1]
	v_pk_fma_f32 v[232:233], v[108:109], v[114:115], v[232:233] op_sel_hi:[1,0,1]
	v_pk_fma_f32 v[234:235], v[96:97], v[118:119], v[122:123] op_sel_hi:[1,0,0]
	v_pk_fma_f32 v[236:237], v[98:99], v[118:119], v[122:123] op_sel_hi:[1,0,0]
	v_fmac_f32_e32 v234, v203, v119
	v_fmac_f32_e32 v235, v96, v119
	v_fmac_f32_e32 v236, v97, v119
	v_fmac_f32_e32 v237, v98, v119
	v_pk_fma_f32 v[234:235], v[202:203], v[120:121], v[234:235] op_sel_hi:[1,0,1]
	v_pk_fma_f32 v[236:237], v[96:97], v[120:121], v[236:237] op_sel_hi:[1,0,1]
	v_pk_mul_f32 v[238:239], v[230:231], v[230:231]
	v_pk_mul_f32 v[240:241], v[232:233], v[232:233]
	v_pk_fma_f32 v[238:239], v[238:239], v[248:249], v[246:247]
	v_pk_fma_f32 v[240:241], v[240:241], v[248:249], v[246:247]
	v_pk_mul_f32 v[238:239], v[230:231], v[238:239]
	v_pk_mul_f32 v[240:241], v[232:233], v[240:241]
	v_exp_f32_e32 v238, v238
	v_exp_f32_e32 v239, v239
	v_exp_f32_e32 v240, v240
	v_exp_f32_e32 v241, v241
	v_pk_add_f32 v[238:239], v[238:239], 1.0 op_sel_hi:[1,0]
	v_pk_add_f32 v[240:241], v[240:241], 1.0 op_sel_hi:[1,0]
	v_rcp_f32_e32 v238, v238
	v_rcp_f32_e32 v239, v239
	v_rcp_f32_e32 v240, v240
	v_rcp_f32_e32 v241, v241
	v_pk_mul_f32 v[230:231], v[230:231], v[234:235]
	v_pk_mul_f32 v[232:233], v[232:233], v[236:237]
	v_pk_mul_f32 v[238:239], v[230:231], v[238:239]
	v_pk_mul_f32 v[240:241], v[232:233], v[240:241]
	v_cvt_pk_bf16_f32 v212, v238, v239
	v_cvt_pk_bf16_f32 v213, v240, v241
	s_mov_b64 vcc, s[30:31]
	s_nop 0
	v_mov_b32_dpp v214, v212 quad_perm:[1,0,3,2] row_mask:0xf bank_mask:0xf
	v_mov_b32_dpp v215, v213 quad_perm:[1,0,3,2] row_mask:0xf bank_mask:0xf
	v_perm_b32 v216, v214, v212, v253
	v_perm_b32 v217, v215, v213, v253
	s_nop 1
	v_mov_b32_dpp v218, v216 quad_perm:[2,3,0,1] row_mask:0xf bank_mask:0xf
	v_mov_b32_dpp v219, v217 quad_perm:[2,3,0,1] row_mask:0xf bank_mask:0xf
	v_cndmask_b32_e32 v180, v216, v219, vcc
	v_cndmask_b32_e32 v181, v218, v217, vcc
	s_waitcnt lgkmcnt(0)
	ds_bpermute_b32 v200, v252, v94
	ds_bpermute_b32 v201, v252, v95
	ds_bpermute_b32 v202, v252, v90
	ds_bpermute_b32 v203, v252, v91
	v_pk_fma_f32 v[230:231], v[36:37], v[124:125], v[128:129] op_sel_hi:[1,0,0]
	v_pk_fma_f32 v[232:233], v[38:39], v[124:125], v[128:129] op_sel_hi:[1,0,0]
	v_fmac_f32_e32 v230, v205, v125
	v_fmac_f32_e32 v231, v36, v125
	v_fmac_f32_e32 v232, v37, v125
	v_fmac_f32_e32 v233, v38, v125
	v_pk_fma_f32 v[230:231], v[204:205], v[126:127], v[230:231] op_sel_hi:[1,0,1]
	v_pk_fma_f32 v[232:233], v[36:37], v[126:127], v[232:233] op_sel_hi:[1,0,1]
	v_pk_fma_f32 v[234:235], v[32:33], v[130:131], v[134:135] op_sel_hi:[1,0,0]
	v_pk_fma_f32 v[236:237], v[34:35], v[130:131], v[134:135] op_sel_hi:[1,0,0]
	v_fmac_f32_e32 v234, v207, v131
	v_fmac_f32_e32 v235, v32, v131
	v_fmac_f32_e32 v236, v33, v131
	v_fmac_f32_e32 v237, v34, v131
	v_pk_fma_f32 v[234:235], v[206:207], v[132:133], v[234:235] op_sel_hi:[1,0,1]
	v_pk_fma_f32 v[236:237], v[32:33], v[132:133], v[236:237] op_sel_hi:[1,0,1]
	v_pk_mul_f32 v[238:239], v[230:231], v[230:231]
	v_pk_mul_f32 v[240:241], v[232:233], v[232:233]
	v_pk_fma_f32 v[238:239], v[238:239], v[248:249], v[246:247]
	v_pk_fma_f32 v[240:241], v[240:241], v[248:249], v[246:247]
	v_pk_mul_f32 v[238:239], v[230:231], v[238:239]
	v_pk_mul_f32 v[240:241], v[232:233], v[240:241]
	v_exp_f32_e32 v238, v238
	v_exp_f32_e32 v239, v239
	v_exp_f32_e32 v240, v240
	v_exp_f32_e32 v241, v241
	v_pk_add_f32 v[238:239], v[238:239], 1.0 op_sel_hi:[1,0]
	v_pk_add_f32 v[240:241], v[240:241], 1.0 op_sel_hi:[1,0]
	v_rcp_f32_e32 v238, v238
	v_rcp_f32_e32 v239, v239
	v_rcp_f32_e32 v240, v240
	v_rcp_f32_e32 v241, v241
	v_pk_mul_f32 v[230:231], v[230:231], v[234:235]
	v_pk_mul_f32 v[232:233], v[232:233], v[236:237]
	v_pk_mul_f32 v[238:239], v[230:231], v[238:239]
	v_pk_mul_f32 v[240:241], v[232:233], v[240:241]
	v_cvt_pk_bf16_f32 v212, v238, v239
	v_cvt_pk_bf16_f32 v213, v240, v241
	s_mov_b64 vcc, s[30:31]
	s_nop 0
	v_mov_b32_dpp v214, v212 quad_perm:[1,0,3,2] row_mask:0xf bank_mask:0xf
	v_mov_b32_dpp v215, v213 quad_perm:[1,0,3,2] row_mask:0xf bank_mask:0xf
	v_perm_b32 v216, v214, v212, v253
	v_perm_b32 v217, v215, v213, v253
	s_nop 1
	v_mov_b32_dpp v218, v216 quad_perm:[2,3,0,1] row_mask:0xf bank_mask:0xf
	v_mov_b32_dpp v219, v217 quad_perm:[2,3,0,1] row_mask:0xf bank_mask:0xf
	v_cndmask_b32_e32 v182, v216, v219, vcc
	v_cndmask_b32_e32 v183, v218, v217, vcc
	s_movk_i32 s15, 0xfd2
	v_cmp_gt_i32_e64 s[24:25], s15, v251
	s_add_u32 s84, s58, 0x3f400
	s_addc_u32 s85, s59, 0
	s_mov_b64 exec, s[24:25]
	global_store_dwordx4 v250, v[180:183], s[84:85] nt
	s_mov_b64 exec, -1
	s_nop 0
	s_waitcnt lgkmcnt(0)
	ds_bpermute_b32 v204, v252, v30
	ds_bpermute_b32 v205, v252, v31
	ds_bpermute_b32 v206, v252, v26
	ds_bpermute_b32 v207, v252, v27
	v_pk_fma_f32 v[230:231], v[92:93], v[112:113], v[116:117] op_sel_hi:[1,0,0]
	v_pk_fma_f32 v[232:233], v[94:95], v[112:113], v[116:117] op_sel_hi:[1,0,0]
	v_fmac_f32_e32 v230, v201, v113
	v_fmac_f32_e32 v231, v92, v113
	v_fmac_f32_e32 v232, v93, v113
	v_fmac_f32_e32 v233, v94, v113
	v_pk_fma_f32 v[230:231], v[200:201], v[114:115], v[230:231] op_sel_hi:[1,0,1]
	v_pk_fma_f32 v[232:233], v[92:93], v[114:115], v[232:233] op_sel_hi:[1,0,1]
	v_pk_fma_f32 v[234:235], v[88:89], v[118:119], v[122:123] op_sel_hi:[1,0,0]
	v_pk_fma_f32 v[236:237], v[90:91], v[118:119], v[122:123] op_sel_hi:[1,0,0]
	v_fmac_f32_e32 v234, v203, v119
	v_fmac_f32_e32 v235, v88, v119
	v_fmac_f32_e32 v236, v89, v119
	v_fmac_f32_e32 v237, v90, v119
	v_pk_fma_f32 v[234:235], v[202:203], v[120:121], v[234:235] op_sel_hi:[1,0,1]
	v_pk_fma_f32 v[236:237], v[88:89], v[120:121], v[236:237] op_sel_hi:[1,0,1]
	v_pk_mul_f32 v[238:239], v[230:231], v[230:231]
	v_pk_mul_f32 v[240:241], v[232:233], v[232:233]
	v_pk_fma_f32 v[238:239], v[238:239], v[248:249], v[246:247]
	v_pk_fma_f32 v[240:241], v[240:241], v[248:249], v[246:247]
	v_pk_mul_f32 v[238:239], v[230:231], v[238:239]
	v_pk_mul_f32 v[240:241], v[232:233], v[240:241]
	v_exp_f32_e32 v238, v238
	v_exp_f32_e32 v239, v239
	v_exp_f32_e32 v240, v240
	v_exp_f32_e32 v241, v241
	v_pk_add_f32 v[238:239], v[238:239], 1.0 op_sel_hi:[1,0]
	v_pk_add_f32 v[240:241], v[240:241], 1.0 op_sel_hi:[1,0]
	v_rcp_f32_e32 v238, v238
	v_rcp_f32_e32 v239, v239
	v_rcp_f32_e32 v240, v240
	v_rcp_f32_e32 v241, v241
	v_pk_mul_f32 v[230:231], v[230:231], v[234:235]
	v_pk_mul_f32 v[232:233], v[232:233], v[236:237]
	v_pk_mul_f32 v[238:239], v[230:231], v[238:239]
	v_pk_mul_f32 v[240:241], v[232:233], v[240:241]
	v_cvt_pk_bf16_f32 v212, v238, v239
	v_cvt_pk_bf16_f32 v213, v240, v241
	s_mov_b64 vcc, s[30:31]
	s_nop 0
	v_mov_b32_dpp v214, v212 quad_perm:[1,0,3,2] row_mask:0xf bank_mask:0xf
	v_mov_b32_dpp v215, v213 quad_perm:[1,0,3,2] row_mask:0xf bank_mask:0xf
	v_perm_b32 v216, v214, v212, v253
	v_perm_b32 v217, v215, v213, v253
	s_nop 1
	v_mov_b32_dpp v218, v216 quad_perm:[2,3,0,1] row_mask:0xf bank_mask:0xf
	v_mov_b32_dpp v219, v217 quad_perm:[2,3,0,1] row_mask:0xf bank_mask:0xf
	v_cndmask_b32_e32 v176, v216, v219, vcc
	v_cndmask_b32_e32 v177, v218, v217, vcc
	s_waitcnt lgkmcnt(0)
	s_mov_b64 vcc, s[28:29]
	v_cndmask_b32_e32 v208, v86, v94, vcc
	v_cndmask_b32_e32 v209, v87, v95, vcc
	v_cndmask_b32_e32 v210, v82, v90, vcc
	v_cndmask_b32_e32 v211, v83, v91, vcc
	ds_bpermute_b32 v200, v252, v208
	ds_bpermute_b32 v201, v252, v209
	ds_bpermute_b32 v202, v252, v210
	ds_bpermute_b32 v203, v252, v211
	v_pk_fma_f32 v[230:231], v[28:29], v[124:125], v[128:129] op_sel_hi:[1,0,0]
	v_pk_fma_f32 v[232:233], v[30:31], v[124:125], v[128:129] op_sel_hi:[1,0,0]
	v_fmac_f32_e32 v230, v205, v125
	v_fmac_f32_e32 v231, v28, v125
	v_fmac_f32_e32 v232, v29, v125
	v_fmac_f32_e32 v233, v30, v125
	v_pk_fma_f32 v[230:231], v[204:205], v[126:127], v[230:231] op_sel_hi:[1,0,1]
	v_pk_fma_f32 v[232:233], v[28:29], v[126:127], v[232:233] op_sel_hi:[1,0,1]
	v_pk_fma_f32 v[234:235], v[24:25], v[130:131], v[134:135] op_sel_hi:[1,0,0]
	v_pk_fma_f32 v[236:237], v[26:27], v[130:131], v[134:135] op_sel_hi:[1,0,0]
	v_fmac_f32_e32 v234, v207, v131
	v_fmac_f32_e32 v235, v24, v131
	v_fmac_f32_e32 v236, v25, v131
	v_fmac_f32_e32 v237, v26, v131
	v_pk_fma_f32 v[234:235], v[206:207], v[132:133], v[234:235] op_sel_hi:[1,0,1]
	v_pk_fma_f32 v[236:237], v[24:25], v[132:133], v[236:237] op_sel_hi:[1,0,1]
	v_pk_mul_f32 v[238:239], v[230:231], v[230:231]
	v_pk_mul_f32 v[240:241], v[232:233], v[232:233]
	v_pk_fma_f32 v[238:239], v[238:239], v[248:249], v[246:247]
	v_pk_fma_f32 v[240:241], v[240:241], v[248:249], v[246:247]
	v_pk_mul_f32 v[238:239], v[230:231], v[238:239]
	v_pk_mul_f32 v[240:241], v[232:233], v[240:241]
	v_exp_f32_e32 v238, v238
	v_exp_f32_e32 v239, v239
	v_exp_f32_e32 v240, v240
	v_exp_f32_e32 v241, v241
	v_pk_add_f32 v[238:239], v[238:239], 1.0 op_sel_hi:[1,0]
	v_pk_add_f32 v[240:241], v[240:241], 1.0 op_sel_hi:[1,0]
	v_rcp_f32_e32 v238, v238
	v_rcp_f32_e32 v239, v239
	v_rcp_f32_e32 v240, v240
	v_rcp_f32_e32 v241, v241
	v_pk_mul_f32 v[230:231], v[230:231], v[234:235]
	v_pk_mul_f32 v[232:233], v[232:233], v[236:237]
	v_pk_mul_f32 v[238:239], v[230:231], v[238:239]
	v_pk_mul_f32 v[240:241], v[232:233], v[240:241]
	v_cvt_pk_bf16_f32 v212, v238, v239
	v_cvt_pk_bf16_f32 v213, v240, v241
	s_mov_b64 vcc, s[30:31]
	s_nop 0
	v_mov_b32_dpp v214, v212 quad_perm:[1,0,3,2] row_mask:0xf bank_mask:0xf
	v_mov_b32_dpp v215, v213 quad_perm:[1,0,3,2] row_mask:0xf bank_mask:0xf
	v_perm_b32 v216, v214, v212, v253
	v_perm_b32 v217, v215, v213, v253
	s_nop 1
	v_mov_b32_dpp v218, v216 quad_perm:[2,3,0,1] row_mask:0xf bank_mask:0xf
	v_mov_b32_dpp v219, v217 quad_perm:[2,3,0,1] row_mask:0xf bank_mask:0xf
	v_cndmask_b32_e32 v178, v216, v219, vcc
	v_cndmask_b32_e32 v179, v218, v217, vcc
	s_movk_i32 s15, 0xf86
	v_cmp_gt_i32_e64 s[24:25], s15, v251
	s_add_u32 s84, s58, 0xa7c00
	s_addc_u32 s85, s59, 0
	s_and_b64 s[24:25], s[24:25], s[36:37]
	s_mov_b64 exec, s[24:25]
	global_store_dwordx4 v250, v[176:179], s[84:85] nt
	s_mov_b64 exec, -1
	s_nop 0
	s_waitcnt lgkmcnt(0)
	s_mov_b64 vcc, s[28:29]
	v_cndmask_b32_e32 v208, v22, v30, vcc
	v_cndmask_b32_e32 v209, v23, v31, vcc
	v_cndmask_b32_e32 v210, v18, v26, vcc
	v_cndmask_b32_e32 v211, v19, v27, vcc
	ds_bpermute_b32 v204, v252, v208
	ds_bpermute_b32 v205, v252, v209
	ds_bpermute_b32 v206, v252, v210
	ds_bpermute_b32 v207, v252, v211
	v_pk_fma_f32 v[230:231], v[84:85], v[112:113], v[116:117] op_sel_hi:[1,0,0]
	v_pk_fma_f32 v[232:233], v[86:87], v[112:113], v[116:117] op_sel_hi:[1,0,0]
	v_fmac_f32_e32 v230, v201, v113
	v_fmac_f32_e32 v231, v84, v113
	v_fmac_f32_e32 v232, v85, v113
	v_fmac_f32_e32 v233, v86, v113
	v_pk_fma_f32 v[230:231], v[200:201], v[114:115], v[230:231] op_sel_hi:[1,0,1]
	v_pk_fma_f32 v[232:233], v[84:85], v[114:115], v[232:233] op_sel_hi:[1,0,1]
	v_pk_fma_f32 v[234:235], v[80:81], v[118:119], v[122:123] op_sel_hi:[1,0,0]
	v_pk_fma_f32 v[236:237], v[82:83], v[118:119], v[122:123] op_sel_hi:[1,0,0]
	v_fmac_f32_e32 v234, v203, v119
	v_fmac_f32_e32 v235, v80, v119
	v_fmac_f32_e32 v236, v81, v119
	v_fmac_f32_e32 v237, v82, v119
	v_pk_fma_f32 v[234:235], v[202:203], v[120:121], v[234:235] op_sel_hi:[1,0,1]
	v_pk_fma_f32 v[236:237], v[80:81], v[120:121], v[236:237] op_sel_hi:[1,0,1]
	v_pk_mul_f32 v[238:239], v[230:231], v[230:231]
	v_pk_mul_f32 v[240:241], v[232:233], v[232:233]
	v_pk_fma_f32 v[238:239], v[238:239], v[248:249], v[246:247]
	v_pk_fma_f32 v[240:241], v[240:241], v[248:249], v[246:247]
	v_pk_mul_f32 v[238:239], v[230:231], v[238:239]
	v_pk_mul_f32 v[240:241], v[232:233], v[240:241]
	v_exp_f32_e32 v238, v238
	v_exp_f32_e32 v239, v239
	v_exp_f32_e32 v240, v240
	v_exp_f32_e32 v241, v241
	v_pk_add_f32 v[238:239], v[238:239], 1.0 op_sel_hi:[1,0]
	v_pk_add_f32 v[240:241], v[240:241], 1.0 op_sel_hi:[1,0]
	v_rcp_f32_e32 v238, v238
	v_rcp_f32_e32 v239, v239
	v_rcp_f32_e32 v240, v240
	v_rcp_f32_e32 v241, v241
	v_pk_mul_f32 v[230:231], v[230:231], v[234:235]
	v_pk_mul_f32 v[232:233], v[232:233], v[236:237]
	v_pk_mul_f32 v[238:239], v[230:231], v[238:239]
	v_pk_mul_f32 v[240:241], v[232:233], v[240:241]
	v_cvt_pk_bf16_f32 v212, v238, v239
	v_cvt_pk_bf16_f32 v213, v240, v241
	s_mov_b64 vcc, s[30:31]
	s_nop 0
	v_mov_b32_dpp v214, v212 quad_perm:[1,0,3,2] row_mask:0xf bank_mask:0xf
	v_mov_b32_dpp v215, v213 quad_perm:[1,0,3,2] row_mask:0xf bank_mask:0xf
	v_perm_b32 v216, v214, v212, v253
	v_perm_b32 v217, v215, v213, v253
	s_nop 1
	v_mov_b32_dpp v218, v216 quad_perm:[2,3,0,1] row_mask:0xf bank_mask:0xf
	v_mov_b32_dpp v219, v217 quad_perm:[2,3,0,1] row_mask:0xf bank_mask:0xf
	v_cndmask_b32_e32 v180, v216, v219, vcc
	v_cndmask_b32_e32 v181, v218, v217, vcc
	s_waitcnt lgkmcnt(0)
	s_mov_b64 vcc, s[28:29]
	v_cndmask_b32_e32 v208, v78, v86, vcc
	v_cndmask_b32_e32 v209, v79, v87, vcc
	v_cndmask_b32_e32 v210, v74, v82, vcc
	v_cndmask_b32_e32 v211, v75, v83, vcc
	ds_bpermute_b32 v200, v252, v208
	ds_bpermute_b32 v201, v252, v209
	ds_bpermute_b32 v202, v252, v210
	ds_bpermute_b32 v203, v252, v211
	v_pk_fma_f32 v[230:231], v[20:21], v[124:125], v[128:129] op_sel_hi:[1,0,0]
	v_pk_fma_f32 v[232:233], v[22:23], v[124:125], v[128:129] op_sel_hi:[1,0,0]
	v_fmac_f32_e32 v230, v205, v125
	v_fmac_f32_e32 v231, v20, v125
	v_fmac_f32_e32 v232, v21, v125
	v_fmac_f32_e32 v233, v22, v125
	v_pk_fma_f32 v[230:231], v[204:205], v[126:127], v[230:231] op_sel_hi:[1,0,1]
	v_pk_fma_f32 v[232:233], v[20:21], v[126:127], v[232:233] op_sel_hi:[1,0,1]
	v_pk_fma_f32 v[234:235], v[16:17], v[130:131], v[134:135] op_sel_hi:[1,0,0]
	v_pk_fma_f32 v[236:237], v[18:19], v[130:131], v[134:135] op_sel_hi:[1,0,0]
	v_fmac_f32_e32 v234, v207, v131
	v_fmac_f32_e32 v235, v16, v131
	v_fmac_f32_e32 v236, v17, v131
	v_fmac_f32_e32 v237, v18, v131
	v_pk_fma_f32 v[234:235], v[206:207], v[132:133], v[234:235] op_sel_hi:[1,0,1]
	v_pk_fma_f32 v[236:237], v[16:17], v[132:133], v[236:237] op_sel_hi:[1,0,1]
	v_pk_mul_f32 v[238:239], v[230:231], v[230:231]
	v_pk_mul_f32 v[240:241], v[232:233], v[232:233]
	v_pk_fma_f32 v[238:239], v[238:239], v[248:249], v[246:247]
	v_pk_fma_f32 v[240:241], v[240:241], v[248:249], v[246:247]
	v_pk_mul_f32 v[238:239], v[230:231], v[238:239]
	v_pk_mul_f32 v[240:241], v[232:233], v[240:241]
	v_exp_f32_e32 v238, v238
	v_exp_f32_e32 v239, v239
	v_exp_f32_e32 v240, v240
	v_exp_f32_e32 v241, v241
	v_pk_add_f32 v[238:239], v[238:239], 1.0 op_sel_hi:[1,0]
	v_pk_add_f32 v[240:241], v[240:241], 1.0 op_sel_hi:[1,0]
	v_rcp_f32_e32 v238, v238
	v_rcp_f32_e32 v239, v239
	v_rcp_f32_e32 v240, v240
	v_rcp_f32_e32 v241, v241
	v_pk_mul_f32 v[230:231], v[230:231], v[234:235]
	v_pk_mul_f32 v[232:233], v[232:233], v[236:237]
	v_pk_mul_f32 v[238:239], v[230:231], v[238:239]
	v_pk_mul_f32 v[240:241], v[232:233], v[240:241]
	v_cvt_pk_bf16_f32 v212, v238, v239
	v_cvt_pk_bf16_f32 v213, v240, v241
	s_mov_b64 vcc, s[30:31]
	s_nop 0
	v_mov_b32_dpp v214, v212 quad_perm:[1,0,3,2] row_mask:0xf bank_mask:0xf
	v_mov_b32_dpp v215, v213 quad_perm:[1,0,3,2] row_mask:0xf bank_mask:0xf
	v_perm_b32 v216, v214, v212, v253
	v_perm_b32 v217, v215, v213, v253
	s_nop 1
	v_mov_b32_dpp v218, v216 quad_perm:[2,3,0,1] row_mask:0xf bank_mask:0xf
	v_mov_b32_dpp v219, v217 quad_perm:[2,3,0,1] row_mask:0xf bank_mask:0xf
	v_cndmask_b32_e32 v182, v216, v219, vcc
	v_cndmask_b32_e32 v183, v218, v217, vcc
	s_movk_i32 s15, 0xf76
	v_cmp_gt_i32_e64 s[24:25], s15, v251
	s_add_u32 s84, s58, 0xbdc00
	s_addc_u32 s85, s59, 0
	s_mov_b64 exec, s[24:25]
	global_store_dwordx4 v250, v[180:183], s[84:85] nt
	s_mov_b64 exec, -1
	s_nop 0
	s_waitcnt lgkmcnt(0)
	s_mov_b64 vcc, s[28:29]
	v_cndmask_b32_e32 v208, v14, v22, vcc
	v_cndmask_b32_e32 v209, v15, v23, vcc
	v_cndmask_b32_e32 v210, v10, v18, vcc
	v_cndmask_b32_e32 v211, v11, v19, vcc
	ds_bpermute_b32 v204, v252, v208
	ds_bpermute_b32 v205, v252, v209
	ds_bpermute_b32 v206, v252, v210
	ds_bpermute_b32 v207, v252, v211
	v_pk_fma_f32 v[230:231], v[76:77], v[112:113], v[116:117] op_sel_hi:[1,0,0]
	v_pk_fma_f32 v[232:233], v[78:79], v[112:113], v[116:117] op_sel_hi:[1,0,0]
	v_fmac_f32_e32 v230, v201, v113
	v_fmac_f32_e32 v231, v76, v113
	v_fmac_f32_e32 v232, v77, v113
	v_fmac_f32_e32 v233, v78, v113
	v_pk_fma_f32 v[230:231], v[200:201], v[114:115], v[230:231] op_sel_hi:[1,0,1]
	v_pk_fma_f32 v[232:233], v[76:77], v[114:115], v[232:233] op_sel_hi:[1,0,1]
	v_pk_fma_f32 v[234:235], v[72:73], v[118:119], v[122:123] op_sel_hi:[1,0,0]
	v_pk_fma_f32 v[236:237], v[74:75], v[118:119], v[122:123] op_sel_hi:[1,0,0]
	v_fmac_f32_e32 v234, v203, v119
	v_fmac_f32_e32 v235, v72, v119
	v_fmac_f32_e32 v236, v73, v119
	v_fmac_f32_e32 v237, v74, v119
	v_pk_fma_f32 v[234:235], v[202:203], v[120:121], v[234:235] op_sel_hi:[1,0,1]
	v_pk_fma_f32 v[236:237], v[72:73], v[120:121], v[236:237] op_sel_hi:[1,0,1]
	v_pk_mul_f32 v[238:239], v[230:231], v[230:231]
	v_pk_mul_f32 v[240:241], v[232:233], v[232:233]
	v_pk_fma_f32 v[238:239], v[238:239], v[248:249], v[246:247]
	v_pk_fma_f32 v[240:241], v[240:241], v[248:249], v[246:247]
	v_pk_mul_f32 v[238:239], v[230:231], v[238:239]
	v_pk_mul_f32 v[240:241], v[232:233], v[240:241]
	v_exp_f32_e32 v238, v238
	v_exp_f32_e32 v239, v239
	v_exp_f32_e32 v240, v240
	v_exp_f32_e32 v241, v241
	v_pk_add_f32 v[238:239], v[238:239], 1.0 op_sel_hi:[1,0]
	v_pk_add_f32 v[240:241], v[240:241], 1.0 op_sel_hi:[1,0]
	v_rcp_f32_e32 v238, v238
	v_rcp_f32_e32 v239, v239
	v_rcp_f32_e32 v240, v240
	v_rcp_f32_e32 v241, v241
	v_pk_mul_f32 v[230:231], v[230:231], v[234:235]
	v_pk_mul_f32 v[232:233], v[232:233], v[236:237]
	v_pk_mul_f32 v[238:239], v[230:231], v[238:239]
	v_pk_mul_f32 v[240:241], v[232:233], v[240:241]
	v_cvt_pk_bf16_f32 v212, v238, v239
	v_cvt_pk_bf16_f32 v213, v240, v241
	s_mov_b64 vcc, s[30:31]
	s_nop 0
	v_mov_b32_dpp v214, v212 quad_perm:[1,0,3,2] row_mask:0xf bank_mask:0xf
	v_mov_b32_dpp v215, v213 quad_perm:[1,0,3,2] row_mask:0xf bank_mask:0xf
	v_perm_b32 v216, v214, v212, v253
	v_perm_b32 v217, v215, v213, v253
	s_nop 1
	v_mov_b32_dpp v218, v216 quad_perm:[2,3,0,1] row_mask:0xf bank_mask:0xf
	v_mov_b32_dpp v219, v217 quad_perm:[2,3,0,1] row_mask:0xf bank_mask:0xf
	v_cndmask_b32_e32 v176, v216, v219, vcc
	v_cndmask_b32_e32 v177, v218, v217, vcc
	s_waitcnt lgkmcnt(0)
	s_mov_b64 vcc, s[28:29]
	v_cndmask_b32_e32 v208, v70, v78, vcc
	v_cndmask_b32_e32 v209, v71, v79, vcc
	v_cndmask_b32_e32 v210, v66, v74, vcc
	v_cndmask_b32_e32 v211, v67, v75, vcc
	ds_bpermute_b32 v200, v252, v208
	ds_bpermute_b32 v201, v252, v209
	ds_bpermute_b32 v202, v252, v210
	ds_bpermute_b32 v203, v252, v211
	v_pk_fma_f32 v[230:231], v[12:13], v[124:125], v[128:129] op_sel_hi:[1,0,0]
	v_pk_fma_f32 v[232:233], v[14:15], v[124:125], v[128:129] op_sel_hi:[1,0,0]
	v_fmac_f32_e32 v230, v205, v125
	v_fmac_f32_e32 v231, v12, v125
	v_fmac_f32_e32 v232, v13, v125
	v_fmac_f32_e32 v233, v14, v125
	v_pk_fma_f32 v[230:231], v[204:205], v[126:127], v[230:231] op_sel_hi:[1,0,1]
	v_pk_fma_f32 v[232:233], v[12:13], v[126:127], v[232:233] op_sel_hi:[1,0,1]
	v_pk_fma_f32 v[234:235], v[8:9], v[130:131], v[134:135] op_sel_hi:[1,0,0]
	v_pk_fma_f32 v[236:237], v[10:11], v[130:131], v[134:135] op_sel_hi:[1,0,0]
	v_fmac_f32_e32 v234, v207, v131
	v_fmac_f32_e32 v235, v8, v131
	v_fmac_f32_e32 v236, v9, v131
	v_fmac_f32_e32 v237, v10, v131
	v_pk_fma_f32 v[234:235], v[206:207], v[132:133], v[234:235] op_sel_hi:[1,0,1]
	v_pk_fma_f32 v[236:237], v[8:9], v[132:133], v[236:237] op_sel_hi:[1,0,1]
	v_pk_mul_f32 v[238:239], v[230:231], v[230:231]
	v_pk_mul_f32 v[240:241], v[232:233], v[232:233]
	v_pk_fma_f32 v[238:239], v[238:239], v[248:249], v[246:247]
	v_pk_fma_f32 v[240:241], v[240:241], v[248:249], v[246:247]
	v_pk_mul_f32 v[238:239], v[230:231], v[238:239]
	v_pk_mul_f32 v[240:241], v[232:233], v[240:241]
	v_exp_f32_e32 v238, v238
	v_exp_f32_e32 v239, v239
	v_exp_f32_e32 v240, v240
	v_exp_f32_e32 v241, v241
	v_pk_add_f32 v[238:239], v[238:239], 1.0 op_sel_hi:[1,0]
	v_pk_add_f32 v[240:241], v[240:241], 1.0 op_sel_hi:[1,0]
	v_rcp_f32_e32 v238, v238
	v_rcp_f32_e32 v239, v239
	v_rcp_f32_e32 v240, v240
	v_rcp_f32_e32 v241, v241
	v_pk_mul_f32 v[230:231], v[230:231], v[234:235]
	v_pk_mul_f32 v[232:233], v[232:233], v[236:237]
	v_pk_mul_f32 v[238:239], v[230:231], v[238:239]
	v_pk_mul_f32 v[240:241], v[232:233], v[240:241]
	v_cvt_pk_bf16_f32 v212, v238, v239
	v_cvt_pk_bf16_f32 v213, v240, v241
	s_mov_b64 vcc, s[30:31]
	s_nop 0
	v_mov_b32_dpp v214, v212 quad_perm:[1,0,3,2] row_mask:0xf bank_mask:0xf
	v_mov_b32_dpp v215, v213 quad_perm:[1,0,3,2] row_mask:0xf bank_mask:0xf
	v_perm_b32 v216, v214, v212, v253
	v_perm_b32 v217, v215, v213, v253
	s_nop 1
	v_mov_b32_dpp v218, v216 quad_perm:[2,3,0,1] row_mask:0xf bank_mask:0xf
	v_mov_b32_dpp v219, v217 quad_perm:[2,3,0,1] row_mask:0xf bank_mask:0xf
	v_cndmask_b32_e32 v178, v216, v219, vcc
	v_cndmask_b32_e32 v179, v218, v217, vcc
	s_movk_i32 s15, 0xf66
	v_cmp_gt_i32_e64 s[24:25], s15, v251
	s_add_u32 s84, s58, 0xd3c00
	s_addc_u32 s85, s59, 0
	s_mov_b64 exec, s[24:25]
	global_store_dwordx4 v250, v[176:179], s[84:85] nt
	s_mov_b64 exec, -1
	s_nop 0
	s_waitcnt lgkmcnt(0)
	s_mov_b64 vcc, s[28:29]
	v_cndmask_b32_e32 v208, v6, v14, vcc
	v_cndmask_b32_e32 v209, v7, v15, vcc
	v_cndmask_b32_e32 v210, v2, v10, vcc
	v_cndmask_b32_e32 v211, v3, v11, vcc
	ds_bpermute_b32 v204, v252, v208
	ds_bpermute_b32 v205, v252, v209
	ds_bpermute_b32 v206, v252, v210
	ds_bpermute_b32 v207, v252, v211
	v_pk_fma_f32 v[230:231], v[68:69], v[112:113], v[116:117] op_sel_hi:[1,0,0]
	v_pk_fma_f32 v[232:233], v[70:71], v[112:113], v[116:117] op_sel_hi:[1,0,0]
	v_fmac_f32_e32 v230, v201, v113
	v_fmac_f32_e32 v231, v68, v113
	v_fmac_f32_e32 v232, v69, v113
	v_fmac_f32_e32 v233, v70, v113
	v_pk_fma_f32 v[230:231], v[200:201], v[114:115], v[230:231] op_sel_hi:[1,0,1]
	v_pk_fma_f32 v[232:233], v[68:69], v[114:115], v[232:233] op_sel_hi:[1,0,1]
	v_pk_fma_f32 v[234:235], v[64:65], v[118:119], v[122:123] op_sel_hi:[1,0,0]
	v_pk_fma_f32 v[236:237], v[66:67], v[118:119], v[122:123] op_sel_hi:[1,0,0]
	v_fmac_f32_e32 v234, v203, v119
	v_fmac_f32_e32 v235, v64, v119
	v_fmac_f32_e32 v236, v65, v119
	v_fmac_f32_e32 v237, v66, v119
	v_pk_fma_f32 v[234:235], v[202:203], v[120:121], v[234:235] op_sel_hi:[1,0,1]
	v_pk_fma_f32 v[236:237], v[64:65], v[120:121], v[236:237] op_sel_hi:[1,0,1]
	v_pk_mul_f32 v[238:239], v[230:231], v[230:231]
	v_pk_mul_f32 v[240:241], v[232:233], v[232:233]
	v_pk_fma_f32 v[238:239], v[238:239], v[248:249], v[246:247]
	v_pk_fma_f32 v[240:241], v[240:241], v[248:249], v[246:247]
	v_pk_mul_f32 v[238:239], v[230:231], v[238:239]
	v_pk_mul_f32 v[240:241], v[232:233], v[240:241]
	v_exp_f32_e32 v238, v238
	v_exp_f32_e32 v239, v239
	v_exp_f32_e32 v240, v240
	v_exp_f32_e32 v241, v241
	v_pk_add_f32 v[238:239], v[238:239], 1.0 op_sel_hi:[1,0]
	v_pk_add_f32 v[240:241], v[240:241], 1.0 op_sel_hi:[1,0]
	v_rcp_f32_e32 v238, v238
	v_rcp_f32_e32 v239, v239
	v_rcp_f32_e32 v240, v240
	v_rcp_f32_e32 v241, v241
	v_pk_mul_f32 v[230:231], v[230:231], v[234:235]
	v_pk_mul_f32 v[232:233], v[232:233], v[236:237]
	v_pk_mul_f32 v[238:239], v[230:231], v[238:239]
	v_pk_mul_f32 v[240:241], v[232:233], v[240:241]
	v_cvt_pk_bf16_f32 v212, v238, v239
	v_cvt_pk_bf16_f32 v213, v240, v241
	s_mov_b64 vcc, s[30:31]
	s_nop 0
	v_mov_b32_dpp v214, v212 quad_perm:[1,0,3,2] row_mask:0xf bank_mask:0xf
	v_mov_b32_dpp v215, v213 quad_perm:[1,0,3,2] row_mask:0xf bank_mask:0xf
	v_perm_b32 v216, v214, v212, v253
	v_perm_b32 v217, v215, v213, v253
	s_nop 1
	v_mov_b32_dpp v218, v216 quad_perm:[2,3,0,1] row_mask:0xf bank_mask:0xf
	v_mov_b32_dpp v219, v217 quad_perm:[2,3,0,1] row_mask:0xf bank_mask:0xf
	v_cndmask_b32_e32 v180, v216, v219, vcc
	v_cndmask_b32_e32 v181, v218, v217, vcc
	s_waitcnt lgkmcnt(0)
	v_pk_fma_f32 v[230:231], v[4:5], v[124:125], v[128:129] op_sel_hi:[1,0,0]
	v_pk_fma_f32 v[232:233], v[6:7], v[124:125], v[128:129] op_sel_hi:[1,0,0]
	v_fmac_f32_e32 v230, v205, v125
	v_fmac_f32_e32 v231, v4, v125
	v_fmac_f32_e32 v232, v5, v125
	v_fmac_f32_e32 v233, v6, v125
	v_pk_fma_f32 v[230:231], v[204:205], v[126:127], v[230:231] op_sel_hi:[1,0,1]
	v_pk_fma_f32 v[232:233], v[4:5], v[126:127], v[232:233] op_sel_hi:[1,0,1]
	v_pk_fma_f32 v[234:235], v[0:1], v[130:131], v[134:135] op_sel_hi:[1,0,0]
	v_pk_fma_f32 v[236:237], v[2:3], v[130:131], v[134:135] op_sel_hi:[1,0,0]
	v_fmac_f32_e32 v234, v207, v131
	v_fmac_f32_e32 v235, v0, v131
	v_fmac_f32_e32 v236, v1, v131
	v_fmac_f32_e32 v237, v2, v131
	v_pk_fma_f32 v[234:235], v[206:207], v[132:133], v[234:235] op_sel_hi:[1,0,1]
	v_pk_fma_f32 v[236:237], v[0:1], v[132:133], v[236:237] op_sel_hi:[1,0,1]
	v_pk_mul_f32 v[238:239], v[230:231], v[230:231]
	v_pk_mul_f32 v[240:241], v[232:233], v[232:233]
	v_pk_fma_f32 v[238:239], v[238:239], v[248:249], v[246:247]
	v_pk_fma_f32 v[240:241], v[240:241], v[248:249], v[246:247]
	v_pk_mul_f32 v[238:239], v[230:231], v[238:239]
	v_pk_mul_f32 v[240:241], v[232:233], v[240:241]
	v_exp_f32_e32 v238, v238
	v_exp_f32_e32 v239, v239
	v_exp_f32_e32 v240, v240
	v_exp_f32_e32 v241, v241
	v_pk_add_f32 v[238:239], v[238:239], 1.0 op_sel_hi:[1,0]
	v_pk_add_f32 v[240:241], v[240:241], 1.0 op_sel_hi:[1,0]
	v_rcp_f32_e32 v238, v238
	v_rcp_f32_e32 v239, v239
	v_rcp_f32_e32 v240, v240
	v_rcp_f32_e32 v241, v241
	v_pk_mul_f32 v[230:231], v[230:231], v[234:235]
	v_pk_mul_f32 v[232:233], v[232:233], v[236:237]
	v_pk_mul_f32 v[238:239], v[230:231], v[238:239]
	v_pk_mul_f32 v[240:241], v[232:233], v[240:241]
	v_cvt_pk_bf16_f32 v212, v238, v239
	v_cvt_pk_bf16_f32 v213, v240, v241
	s_mov_b64 vcc, s[30:31]
	s_nop 0
	v_mov_b32_dpp v214, v212 quad_perm:[1,0,3,2] row_mask:0xf bank_mask:0xf
	v_mov_b32_dpp v215, v213 quad_perm:[1,0,3,2] row_mask:0xf bank_mask:0xf
	v_perm_b32 v216, v214, v212, v253
	v_perm_b32 v217, v215, v213, v253
	s_nop 1
	v_mov_b32_dpp v218, v216 quad_perm:[2,3,0,1] row_mask:0xf bank_mask:0xf
	v_mov_b32_dpp v219, v217 quad_perm:[2,3,0,1] row_mask:0xf bank_mask:0xf
	v_cndmask_b32_e32 v182, v216, v219, vcc
	v_cndmask_b32_e32 v183, v218, v217, vcc
	s_movk_i32 s15, 0xf56
	v_cmp_gt_i32_e64 s[24:25], s15, v251
	s_add_u32 s84, s58, 0xe9c00
	s_addc_u32 s85, s59, 0
	s_mov_b64 exec, s[24:25]
	global_store_dwordx4 v250, v[180:183], s[84:85] nt
	s_mov_b64 exec, -1
	s_nop 0
	s_mov_b64 s[0:1], -1
	s_branch .LBB0_619
	s_nop 0
	s_nop 0
	s_nop 0
	s_nop 0
	s_nop 0
	s_nop 0
	s_nop 0
	s_nop 0
	s_nop 0
	s_nop 0
	s_nop 0
	s_nop 0
	s_nop 0
	s_nop 0
	s_nop 0
	s_nop 0
	s_nop 0
	s_nop 0
	s_nop 0
	s_nop 0
	s_nop 0
	s_nop 0
	s_nop 0
	s_nop 0
	s_nop 0
	s_nop 0
	s_nop 0
	s_nop 0
	s_nop 0
	s_nop 0
	s_nop 0
	s_nop 0
	s_nop 0
	s_nop 0
	s_nop 0
	s_nop 0
	s_nop 0
	s_nop 0
	s_nop 0
	s_nop 0
	s_nop 0
	s_nop 0
	s_nop 0
	s_nop 0
	s_nop 0
	s_nop 0
	s_nop 0
	s_nop 0
	s_nop 0
	s_nop 0
	s_nop 0
	s_nop 0
	s_nop 0
	s_nop 0
	s_nop 0
	s_nop 0
	s_nop 0
	s_nop 0
	s_nop 0
	s_nop 0
	s_nop 0
	s_nop 0
	s_nop 0
	s_nop 0
	s_nop 0
	s_nop 0
	s_nop 0
	s_nop 0
	s_nop 0
	s_nop 0
	s_nop 0
	s_nop 0
	s_nop 0
	s_nop 0
	s_nop 0
	s_nop 0
	s_nop 0
	s_nop 0
	s_nop 0
	s_nop 0
	s_nop 0
	s_nop 0
	s_nop 0
	s_nop 0
	s_nop 0
	s_nop 0
	s_nop 0
	s_nop 0
	s_nop 0
	s_nop 0
	s_nop 0
	s_nop 0
	s_nop 0
	s_nop 0
	s_nop 0
	s_nop 0
	s_nop 0
	s_nop 0
	s_nop 0
	s_nop 0
	s_nop 0
	s_nop 0
	s_nop 0
	s_nop 0
	s_nop 0
	s_nop 0
	s_nop 0
	s_nop 0
	s_nop 0
	s_nop 0
	s_nop 0
	s_nop 0
	s_nop 0
	s_nop 0
	s_nop 0
	s_nop 0
	s_nop 0
	s_nop 0
	s_nop 0
	s_nop 0
	s_nop 0
	s_nop 0
	s_nop 0
	s_nop 0
	s_nop 0
	s_nop 0
	s_nop 0
	s_nop 0
	s_nop 0
	s_nop 0
	s_nop 0
	s_nop 0
	s_nop 0
	s_nop 0
	s_nop 0
	s_nop 0
	s_nop 0
	s_nop 0
	s_nop 0
	s_nop 0
	s_nop 0
	s_nop 0
	s_nop 0
	s_nop 0
	s_nop 0
	s_nop 0
	s_nop 0
	s_nop 0
	s_nop 0
	s_nop 0
	s_nop 0
	s_nop 0
	s_nop 0
	s_nop 0
	s_nop 0
	s_nop 0
	s_nop 0
	s_nop 0
	s_nop 0
	s_nop 0
	s_nop 0
	s_nop 0
	s_nop 0
	s_nop 0
	s_nop 0
	s_nop 0
	s_nop 0
	s_nop 0
	s_nop 0
	s_nop 0
	s_nop 0
	s_nop 0
	s_nop 0
	s_nop 0
	s_nop 0
	s_nop 0
	s_nop 0
	s_nop 0
	s_nop 0
	s_nop 0
	s_nop 0
	s_nop 0
	s_nop 0
	s_nop 0
	s_nop 0
	s_nop 0
	s_nop 0
	s_nop 0
	s_nop 0
	s_nop 0
	s_nop 0
	s_nop 0
	s_nop 0
	s_nop 0
	s_nop 0
	s_nop 0
	s_nop 0
	s_nop 0
	s_nop 0
	s_nop 0
	s_nop 0
	s_nop 0
	s_nop 0
	s_nop 0
	s_nop 0
	s_nop 0
	s_nop 0
	s_nop 0
	s_nop 0
	s_nop 0
	s_nop 0
	s_nop 0
	s_nop 0
	s_nop 0
	s_nop 0
	s_nop 0
	s_nop 0
	s_nop 0
	s_nop 0
	s_nop 0
	s_nop 0
	s_nop 0
	s_nop 0
	s_nop 0
	s_nop 0
	s_nop 0
